# weight conversion items: transposing LDS read phase keeps 8 ds_read2 in flight (was 32 serialized lgkmcnt(0) round trips)
# speedup vs baseline: 1.0163x; 1.0016x over previous
; #define LAS __attribute__((address_space(3)))
; __device__ __forceinline__ unsigned cvt_pk_bf16(float lo, float hi) { unsigned r; asm volatile("v_cvt_pk_bf16_f32 %0, %1, %2" : "=v"(r) : "v"(lo), "v"(hi)); return r; }
; template <bool UPPERM> __device__ __forceinline__ void p0_transpose_item(const float* W, int K, int N, bf16_t* WT, const float* gk, LAS float* scr, int item, int lane) {
;     ...
;     for (int i = 0; i < 16; ++i) { LAS float* d = scr + (4 * i + r4) * 65 + c4; d[0] = v[i][0]; d[1] = v[i][1]; d[2] = v[i][2]; d[3] = v[i][3]; }
;     asm volatile("s_waitcnt lgkmcnt(0)" ::: "memory");
;     const int c = lane & 7;
; #pragma unroll
;     for (int j = 0; j < 8; ++j) { const int n = (lane >> 3) + 8 * j; const LAS float* s = scr + (8 * c) * 65 + n;
;         u32x4 o; o.x = cvt_pk_bf16(s[0 * 65], s[1 * 65]); o.y = cvt_pk_bf16(s[2 * 65], s[3 * 65]); o.z = cvt_pk_bf16(s[4 * 65], s[5 * 65]); o.w = cvt_pk_bf16(s[6 * 65], s[7 * 65]);
;         *(u32x4*)(WT + (size_t)(dn0 + (UPPERM ? ((n >> 5) * 64 + (n & 31)) : n)) * K + k0 + 8 * c) = o; }
.LBB0_31:
	v_add_u32_e32 v68, v73, v74
	s_waitcnt vmcnt(15)
	ds_write2_b32 v68, v4, v5 offset1:1
	ds_write2_b32 v68, v6, v7 offset0:2 offset1:3
	v_add_u32_e32 v4, 0x410, v68
	s_waitcnt vmcnt(14)
	ds_write2_b32 v4, v0, v1 offset1:1
	v_add_u32_e32 v0, 0x418, v68
	ds_write2_b32 v0, v2, v3 offset1:1
	v_add_u32_e32 v0, 0x820, v68
	s_waitcnt vmcnt(13)
	ds_write2_b32 v0, v12, v13 offset1:1
	v_add_u32_e32 v0, 0x828, v68
	ds_write2_b32 v0, v14, v15 offset1:1
	v_add_u32_e32 v0, 0xc30, v68
	s_waitcnt vmcnt(12)
	ds_write2_b32 v0, v8, v9 offset1:1
	v_add_u32_e32 v0, 0xc38, v68
	ds_write2_b32 v0, v10, v11 offset1:1
	v_add_u32_e32 v0, 0x1040, v68
	s_waitcnt vmcnt(11)
	ds_write2_b32 v0, v20, v21 offset1:1
	v_add_u32_e32 v0, 0x1048, v68
	ds_write2_b32 v0, v22, v23 offset1:1
	v_add_u32_e32 v0, 0x1450, v68
	s_waitcnt vmcnt(10)
	ds_write2_b32 v0, v16, v17 offset1:1
	v_add_u32_e32 v0, 0x1458, v68
	ds_write2_b32 v0, v18, v19 offset1:1
	v_add_u32_e32 v0, 0x1860, v68
	s_waitcnt vmcnt(9)
	ds_write2_b32 v0, v28, v29 offset1:1
	v_add_u32_e32 v0, 0x1868, v68
	ds_write2_b32 v0, v30, v31 offset1:1
	v_add_u32_e32 v0, 0x1c70, v68
	s_waitcnt vmcnt(8)
	ds_write2_b32 v0, v24, v25 offset1:1
	v_add_u32_e32 v0, 0x1c78, v68
	ds_write2_b32 v0, v26, v27 offset1:1
	v_add_u32_e32 v0, 0x2080, v68
	s_waitcnt vmcnt(7)
	ds_write2_b32 v0, v36, v37 offset1:1
	v_add_u32_e32 v0, 0x2088, v68
	ds_write2_b32 v0, v38, v39 offset1:1
	v_add_u32_e32 v0, 0x2490, v68
	s_waitcnt vmcnt(6)
	ds_write2_b32 v0, v32, v33 offset1:1
	v_add_u32_e32 v0, 0x2498, v68
	ds_write2_b32 v0, v34, v35 offset1:1
	v_add_u32_e32 v0, 0x28a0, v68
	s_waitcnt vmcnt(5)
	ds_write2_b32 v0, v56, v57 offset1:1
	v_add_u32_e32 v0, 0x28a8, v68
	ds_write2_b32 v0, v58, v59 offset1:1
	v_add_u32_e32 v0, 0x2cb0, v68
	s_waitcnt vmcnt(4)
	ds_write2_b32 v0, v48, v49 offset1:1
	v_add_u32_e32 v0, 0x2cb8, v68
	ds_write2_b32 v0, v50, v51 offset1:1
	v_add_u32_e32 v0, 0x30c0, v68
	s_waitcnt vmcnt(3)
	ds_write2_b32 v0, v60, v61 offset1:1
	v_add_u32_e32 v0, 0x30c8, v68
	ds_write2_b32 v0, v62, v63 offset1:1
	v_add_u32_e32 v0, 0x34d0, v68
	s_waitcnt vmcnt(2)
	ds_write2_b32 v0, v52, v53 offset1:1
	v_add_u32_e32 v0, 0x34d8, v68
	ds_write2_b32 v0, v54, v55 offset1:1
	v_add_u32_e32 v0, 0x38e0, v68
	s_waitcnt vmcnt(1)
	ds_write2_b32 v0, v44, v45 offset1:1
	v_add_u32_e32 v0, 0x38e8, v68
	ds_write2_b32 v0, v46, v47 offset1:1
	v_add_u32_e32 v0, 0x3cf0, v68
	s_lshl_b32 s5, s25, 7
	s_waitcnt vmcnt(0)
	ds_write2_b32 v0, v40, v41 offset1:1
	v_add_u32_e32 v0, 0x3cf8, v68
	s_add_i32 s6, s5, 0x7fffd500
	ds_write2_b32 v0, v42, v43 offset1:1
	s_and_b32 s6, s6, 0x7fffff00
	s_and_b32 s7, s5, 0x80
	s_waitcnt lgkmcnt(0)
	s_or_b32 s6, s7, s6
	v_add_u32_e32 v10, 0x400, v76
	ds_read2_b32 v[142:143], v76 offset1:65
	ds_read2_b32 v[144:145], v76 offset0:130 offset1:195
	ds_read2_b32 v[146:147], v10 offset0:4 offset1:69
	ds_read2_b32 v[148:149], v10 offset0:134 offset1:199
	ds_read2_b32 v[150:151], v76 offset0:8 offset1:73
	ds_read2_b32 v[152:153], v76 offset0:138 offset1:203
	ds_read2_b32 v[154:155], v10 offset0:12 offset1:77
	ds_read2_b32 v[156:157], v10 offset0:142 offset1:207
	s_or_b32 s6, s6, 32
	s_waitcnt lgkmcnt(7)
	v_cvt_pk_bf16_f32 v0, v142, v143
	ds_read2_b32 v[142:143], v76 offset0:16 offset1:81
	s_cmpk_lt_i32 s25, 0x56
	s_waitcnt lgkmcnt(7)
	v_cvt_pk_bf16_f32 v1, v144, v145
	ds_read2_b32 v[144:145], v76 offset0:146 offset1:211
	s_cselect_b32 s6, s5, s6
	s_ashr_i32 s5, s4, 31
	s_lshl_b64 s[4:5], s[4:5], 1
	s_waitcnt lgkmcnt(7)
	v_cvt_pk_bf16_f32 v2, v146, v147
	ds_read2_b32 v[146:147], v10 offset0:20 offset1:85
	s_add_u32 s0, s0, s4
	s_waitcnt lgkmcnt(7)
	v_cvt_pk_bf16_f32 v3, v148, v149
	ds_read2_b32 v[148:149], v10 offset0:150 offset1:215
	v_or_b32_e32 v4, s6, v75
	s_addc_u32 s1, s1, s5
	v_lshlrev_b32_e32 v6, 1, v66
	v_mov_b32_e32 v7, v65
	v_ashrrev_i32_e32 v5, 31, v4
	v_lshl_add_u64 v[6:7], s[0:1], 0, v[6:7]
	v_lshlrev_b64 v[4:5], 12, v[4:5]
	v_lshl_add_u64 v[4:5], v[6:7], 0, v[4:5]
	global_store_dwordx4 v[4:5], v[0:3], off
	s_or_b32 s0, s6, 64
	s_waitcnt lgkmcnt(7)
; #define LAS __attribute__((address_space(3)))
; __device__ __forceinline__ unsigned cvt_pk_bf16(float lo, float hi) { unsigned r; asm volatile("v_cvt_pk_bf16_f32 %0, %1, %2" : "=v"(r) : "v"(lo), "v"(hi)); return r; }
; template <bool UPPERM> __device__ __forceinline__ void p0_transpose_item(const float* W, int K, int N, bf16_t* WT, const float* gk, LAS float* scr, int item, int lane) {
;     ...
;     for (int j = 0; j < 8; ++j) { const int n = (lane >> 3) + 8 * j; const LAS float* s = scr + (8 * c) * 65 + n;
;         u32x4 o; o.x = cvt_pk_bf16(s[0 * 65], s[1 * 65]); o.y = cvt_pk_bf16(s[2 * 65], s[3 * 65]); o.z = cvt_pk_bf16(s[4 * 65], s[5 * 65]); o.w = cvt_pk_bf16(s[6 * 65], s[7 * 65]);
;         *(u32x4*)(WT + (size_t)(dn0 + (UPPERM ? ((n >> 5) * 64 + (n & 31)) : n)) * K + k0 + 8 * c) = o; }
;     asm volatile("s_waitcnt lgkmcnt(0)" ::: "memory");
	v_cvt_pk_bf16_f32 v0, v150, v151
	ds_read2_b32 v[150:151], v76 offset0:24 offset1:89
	s_waitcnt lgkmcnt(7)
	v_cvt_pk_bf16_f32 v1, v152, v153
	ds_read2_b32 v[152:153], v76 offset0:154 offset1:219
	s_waitcnt lgkmcnt(7)
	v_cvt_pk_bf16_f32 v2, v154, v155
	ds_read2_b32 v[154:155], v10 offset0:28 offset1:93
	s_waitcnt lgkmcnt(7)
	v_cvt_pk_bf16_f32 v3, v156, v157
	ds_read2_b32 v[156:157], v10 offset0:158 offset1:223
	v_or_b32_e32 v4, s6, v77
	v_ashrrev_i32_e32 v5, 31, v4
	v_lshlrev_b64 v[4:5], 12, v[4:5]
	v_lshl_add_u64 v[4:5], v[6:7], 0, v[4:5]
	global_store_dwordx4 v[4:5], v[0:3], off
	s_nop 0
	s_waitcnt lgkmcnt(7)
	v_cvt_pk_bf16_f32 v0, v142, v143
	ds_read2_b32 v[142:143], v76 offset0:32 offset1:97
	s_waitcnt lgkmcnt(7)
	v_cvt_pk_bf16_f32 v1, v144, v145
	ds_read2_b32 v[144:145], v76 offset0:162 offset1:227
	s_waitcnt lgkmcnt(7)
	v_cvt_pk_bf16_f32 v2, v146, v147
	ds_read2_b32 v[146:147], v10 offset0:36 offset1:101
	s_waitcnt lgkmcnt(7)
	v_cvt_pk_bf16_f32 v3, v148, v149
	ds_read2_b32 v[148:149], v10 offset0:166 offset1:231
	v_or_b32_e32 v4, s6, v78
	v_ashrrev_i32_e32 v5, 31, v4
	v_lshlrev_b64 v[4:5], 12, v[4:5]
	v_lshl_add_u64 v[4:5], v[6:7], 0, v[4:5]
	global_store_dwordx4 v[4:5], v[0:3], off
	s_nop 0
	s_waitcnt lgkmcnt(7)
	v_cvt_pk_bf16_f32 v0, v150, v151
	ds_read2_b32 v[150:151], v76 offset0:40 offset1:105
	s_waitcnt lgkmcnt(7)
	v_cvt_pk_bf16_f32 v1, v152, v153
	ds_read2_b32 v[152:153], v76 offset0:170 offset1:235
	s_waitcnt lgkmcnt(7)
	v_cvt_pk_bf16_f32 v2, v154, v155
	ds_read2_b32 v[154:155], v10 offset0:44 offset1:109
	s_waitcnt lgkmcnt(7)
	v_cvt_pk_bf16_f32 v3, v156, v157
	ds_read2_b32 v[156:157], v10 offset0:174 offset1:239
	v_or_b32_e32 v4, s6, v79
	v_ashrrev_i32_e32 v5, 31, v4
	v_lshlrev_b64 v[4:5], 12, v[4:5]
	v_lshl_add_u64 v[4:5], v[6:7], 0, v[4:5]
	global_store_dwordx4 v[4:5], v[0:3], off
	s_nop 0
	s_waitcnt lgkmcnt(7)
	v_cvt_pk_bf16_f32 v0, v142, v143
	ds_read2_b32 v[142:143], v76 offset0:48 offset1:113
	s_waitcnt lgkmcnt(7)
	v_cvt_pk_bf16_f32 v1, v144, v145
	ds_read2_b32 v[144:145], v76 offset0:178 offset1:243
	s_waitcnt lgkmcnt(7)
	v_cvt_pk_bf16_f32 v2, v146, v147
	ds_read2_b32 v[146:147], v10 offset0:52 offset1:117
	s_waitcnt lgkmcnt(7)
	v_cvt_pk_bf16_f32 v3, v148, v149
	ds_read2_b32 v[148:149], v10 offset0:182 offset1:247
	v_or_b32_e32 v4, s0, v75
	v_ashrrev_i32_e32 v5, 31, v4
	v_lshlrev_b64 v[4:5], 12, v[4:5]
	v_lshl_add_u64 v[4:5], v[6:7], 0, v[4:5]
	global_store_dwordx4 v[4:5], v[0:3], off
	s_nop 0
	s_waitcnt lgkmcnt(7)
	v_cvt_pk_bf16_f32 v0, v150, v151
	ds_read2_b32 v[150:151], v76 offset0:56 offset1:121
	s_waitcnt lgkmcnt(7)
	v_cvt_pk_bf16_f32 v1, v152, v153
	ds_read2_b32 v[152:153], v76 offset0:186 offset1:251
	s_waitcnt lgkmcnt(7)
	v_cvt_pk_bf16_f32 v2, v154, v155
	ds_read2_b32 v[154:155], v10 offset0:60 offset1:125
	s_waitcnt lgkmcnt(7)
	v_cvt_pk_bf16_f32 v3, v156, v157
	ds_read2_b32 v[156:157], v10 offset0:190 offset1:255
	v_or_b32_e32 v4, s0, v84
	v_ashrrev_i32_e32 v5, 31, v4
	v_lshlrev_b64 v[4:5], 12, v[4:5]
	v_lshl_add_u64 v[4:5], v[6:7], 0, v[4:5]
	global_store_dwordx4 v[4:5], v[0:3], off
	s_nop 0
	s_waitcnt lgkmcnt(7)
	v_cvt_pk_bf16_f32 v0, v142, v143
	s_waitcnt lgkmcnt(6)
	v_cvt_pk_bf16_f32 v1, v144, v145
	s_waitcnt lgkmcnt(5)
	v_cvt_pk_bf16_f32 v2, v146, v147
	s_waitcnt lgkmcnt(4)
	v_cvt_pk_bf16_f32 v3, v148, v149
	v_or_b32_e32 v4, s0, v85
	v_ashrrev_i32_e32 v5, 31, v4
	v_lshlrev_b64 v[4:5], 12, v[4:5]
	v_lshl_add_u64 v[4:5], v[6:7], 0, v[4:5]
	global_store_dwordx4 v[4:5], v[0:3], off
	s_nop 0
	s_waitcnt lgkmcnt(3)
	v_cvt_pk_bf16_f32 v0, v150, v151
	s_waitcnt lgkmcnt(2)
	v_cvt_pk_bf16_f32 v1, v152, v153
	s_waitcnt lgkmcnt(1)
	v_cvt_pk_bf16_f32 v2, v154, v155
	s_waitcnt lgkmcnt(0)
	v_cvt_pk_bf16_f32 v3, v156, v157
	v_or_b32_e32 v4, s0, v86
	v_ashrrev_i32_e32 v5, 31, v4
	v_lshlrev_b64 v[4:5], 12, v[4:5]
	v_lshl_add_u64 v[4:5], v[6:7], 0, v[4:5]
	global_store_dwordx4 v[4:5], v[0:3], off
	s_waitcnt lgkmcnt(0)

; #define LAS __attribute__((address_space(3)))
; __device__ __forceinline__ unsigned cvt_pk_bf16(float lo, float hi) { unsigned r; asm volatile("v_cvt_pk_bf16_f32 %0, %1, %2" : "=v"(r) : "v"(lo), "v"(hi)); return r; }
; template <bool UPPERM> __device__ __forceinline__ void p0_transpose_item(const float* W, int K, int N, bf16_t* WT, const float* gk, LAS float* scr, int item, int lane) {
;     ...
;     for (int i = 0; i < 16; ++i) { LAS float* d = scr + (4 * i + r4) * 65 + c4; d[0] = v[i][0]; d[1] = v[i][1]; d[2] = v[i][2]; d[3] = v[i][3]; }
;     asm volatile("s_waitcnt lgkmcnt(0)" ::: "memory");
;     const int c = lane & 7;
; #pragma unroll
;     for (int j = 0; j < 8; ++j) { const int n = (lane >> 3) + 8 * j; const LAS float* s = scr + (8 * c) * 65 + n;
;         u32x4 o; o.x = cvt_pk_bf16(s[0 * 65], s[1 * 65]); o.y = cvt_pk_bf16(s[2 * 65], s[3 * 65]); o.z = cvt_pk_bf16(s[4 * 65], s[5 * 65]); o.w = cvt_pk_bf16(s[6 * 65], s[7 * 65]);
;         *(u32x4*)(WT + (size_t)(dn0 + (UPPERM ? ((n >> 5) * 64 + (n & 31)) : n)) * K + k0 + 8 * c) = o; }
.LBB0_49:
	v_add_u32_e32 v69, v73, v74
	s_waitcnt vmcnt(15)
	ds_write2_b32 v69, v4, v5 offset1:1
	ds_write2_b32 v69, v6, v7 offset0:2 offset1:3
	v_add_u32_e32 v4, 0x410, v69
	s_waitcnt vmcnt(14)
	ds_write2_b32 v4, v0, v1 offset1:1
	v_add_u32_e32 v0, 0x418, v69
	ds_write2_b32 v0, v2, v3 offset1:1
	v_add_u32_e32 v0, 0x820, v69
	s_waitcnt vmcnt(13)
	ds_write2_b32 v0, v12, v13 offset1:1
	v_add_u32_e32 v0, 0x828, v69
	ds_write2_b32 v0, v14, v15 offset1:1
	v_add_u32_e32 v0, 0xc30, v69
	s_waitcnt vmcnt(12)
	ds_write2_b32 v0, v8, v9 offset1:1
	v_add_u32_e32 v0, 0xc38, v69
	ds_write2_b32 v0, v10, v11 offset1:1
	v_add_u32_e32 v0, 0x1040, v69
	s_waitcnt vmcnt(11)
	ds_write2_b32 v0, v20, v21 offset1:1
	v_add_u32_e32 v0, 0x1048, v69
	ds_write2_b32 v0, v22, v23 offset1:1
	v_add_u32_e32 v0, 0x1450, v69
	s_waitcnt vmcnt(10)
	ds_write2_b32 v0, v16, v17 offset1:1
	v_add_u32_e32 v0, 0x1458, v69
	ds_write2_b32 v0, v18, v19 offset1:1
	v_add_u32_e32 v0, 0x1860, v69
	s_waitcnt vmcnt(9)
	ds_write2_b32 v0, v28, v29 offset1:1
	v_add_u32_e32 v0, 0x1868, v69
	ds_write2_b32 v0, v30, v31 offset1:1
	v_add_u32_e32 v0, 0x1c70, v69
	s_waitcnt vmcnt(8)
	ds_write2_b32 v0, v24, v25 offset1:1
	v_add_u32_e32 v0, 0x1c78, v69
	ds_write2_b32 v0, v26, v27 offset1:1
	v_add_u32_e32 v0, 0x2080, v69
	s_waitcnt vmcnt(7)
	ds_write2_b32 v0, v36, v37 offset1:1
	v_add_u32_e32 v0, 0x2088, v69
	ds_write2_b32 v0, v38, v39 offset1:1
	v_add_u32_e32 v0, 0x2490, v69
	s_waitcnt vmcnt(6)
	ds_write2_b32 v0, v32, v33 offset1:1
	v_add_u32_e32 v0, 0x2498, v69
	ds_write2_b32 v0, v34, v35 offset1:1
	v_add_u32_e32 v0, 0x28a0, v69
	s_waitcnt vmcnt(5)
	ds_write2_b32 v0, v44, v45 offset1:1
	v_add_u32_e32 v0, 0x28a8, v69
	ds_write2_b32 v0, v46, v47 offset1:1
	v_add_u32_e32 v0, 0x2cb0, v69
	s_waitcnt vmcnt(4)
	ds_write2_b32 v0, v40, v41 offset1:1
	v_add_u32_e32 v0, 0x2cb8, v69
	ds_write2_b32 v0, v42, v43 offset1:1
	v_add_u32_e32 v0, 0x30c0, v69
	s_waitcnt vmcnt(3)
	ds_write2_b32 v0, v52, v53 offset1:1
	v_add_u32_e32 v0, 0x30c8, v69
	ds_write2_b32 v0, v54, v55 offset1:1
	v_add_u32_e32 v0, 0x34d0, v69
	s_waitcnt vmcnt(2)
	ds_write2_b32 v0, v48, v49 offset1:1
	v_add_u32_e32 v0, 0x34d8, v69
	ds_write2_b32 v0, v50, v51 offset1:1
	v_add_u32_e32 v0, 0x38e0, v69
	s_waitcnt vmcnt(1)
	ds_write2_b32 v0, v60, v61 offset1:1
	v_add_u32_e32 v0, 0x38e8, v69
	ds_write2_b32 v0, v62, v63 offset1:1
	v_add_u32_e32 v0, 0x3cf0, v69
	s_waitcnt vmcnt(0)
	ds_write2_b32 v0, v56, v57 offset1:1
	v_add_u32_e32 v0, 0x3cf8, v69
	ds_write2_b32 v0, v58, v59 offset1:1
	s_waitcnt lgkmcnt(0)
	v_add_u32_e32 v10, 0x400, v76
	ds_read2_b32 v[142:143], v76 offset1:65
	ds_read2_b32 v[144:145], v76 offset0:130 offset1:195
	ds_read2_b32 v[146:147], v10 offset0:4 offset1:69
	ds_read2_b32 v[148:149], v10 offset0:134 offset1:199
	ds_read2_b32 v[150:151], v76 offset0:8 offset1:73
	ds_read2_b32 v[152:153], v76 offset0:138 offset1:203
	ds_read2_b32 v[154:155], v10 offset0:12 offset1:77
	ds_read2_b32 v[156:157], v10 offset0:142 offset1:207
	s_waitcnt lgkmcnt(7)
	v_cvt_pk_bf16_f32 v0, v142, v143
	ds_read2_b32 v[142:143], v76 offset0:16 offset1:81
	s_waitcnt lgkmcnt(7)
	v_cvt_pk_bf16_f32 v1, v144, v145
	ds_read2_b32 v[144:145], v76 offset0:146 offset1:211
	s_ashr_i32 s5, s4, 31
	s_lshl_b64 s[18:19], s[4:5], 1
	s_waitcnt lgkmcnt(7)
	v_cvt_pk_bf16_f32 v2, v146, v147
	ds_read2_b32 v[146:147], v10 offset0:20 offset1:85
	s_add_u32 s18, s0, s18
	s_waitcnt lgkmcnt(7)
	v_cvt_pk_bf16_f32 v3, v148, v149
	ds_read2_b32 v[148:149], v10 offset0:150 offset1:215
	v_or_b32_e32 v4, s16, v75
	s_addc_u32 s19, s1, s19
	v_lshlrev_b32_e32 v6, 1, v66
	v_mov_b32_e32 v7, v65
	v_ashrrev_i32_e32 v5, 31, v4
	v_lshl_add_u64 v[6:7], s[18:19], 0, v[6:7]
	v_lshlrev_b64 v[4:5], 12, v[4:5]
	v_lshl_add_u64 v[4:5], v[6:7], 0, v[4:5]
	global_store_dwordx4 v[4:5], v[0:3], off
	s_nop 0
	s_waitcnt lgkmcnt(7)
	v_cvt_pk_bf16_f32 v0, v150, v151
	ds_read2_b32 v[150:151], v76 offset0:24 offset1:89
	s_waitcnt lgkmcnt(7)
; #define LAS __attribute__((address_space(3)))
; __device__ __forceinline__ unsigned cvt_pk_bf16(float lo, float hi) { unsigned r; asm volatile("v_cvt_pk_bf16_f32 %0, %1, %2" : "=v"(r) : "v"(lo), "v"(hi)); return r; }
; template <bool UPPERM> __device__ __forceinline__ void p0_transpose_item(const float* W, int K, int N, bf16_t* WT, const float* gk, LAS float* scr, int item, int lane) {
;     ...
;     for (int j = 0; j < 8; ++j) { const int n = (lane >> 3) + 8 * j; const LAS float* s = scr + (8 * c) * 65 + n;
;         u32x4 o; o.x = cvt_pk_bf16(s[0 * 65], s[1 * 65]); o.y = cvt_pk_bf16(s[2 * 65], s[3 * 65]); o.z = cvt_pk_bf16(s[4 * 65], s[5 * 65]); o.w = cvt_pk_bf16(s[6 * 65], s[7 * 65]);
;         *(u32x4*)(WT + (size_t)(dn0 + (UPPERM ? ((n >> 5) * 64 + (n & 31)) : n)) * K + k0 + 8 * c) = o; }
;     asm volatile("s_waitcnt lgkmcnt(0)" ::: "memory");
	v_cvt_pk_bf16_f32 v1, v152, v153
	ds_read2_b32 v[152:153], v76 offset0:154 offset1:219
	s_waitcnt lgkmcnt(7)
	v_cvt_pk_bf16_f32 v2, v154, v155
	ds_read2_b32 v[154:155], v10 offset0:28 offset1:93
	s_waitcnt lgkmcnt(7)
	v_cvt_pk_bf16_f32 v3, v156, v157
	ds_read2_b32 v[156:157], v10 offset0:158 offset1:223
	v_or_b32_e32 v4, s16, v77
	v_ashrrev_i32_e32 v5, 31, v4
	v_lshlrev_b64 v[4:5], 12, v[4:5]
	v_lshl_add_u64 v[4:5], v[6:7], 0, v[4:5]
	global_store_dwordx4 v[4:5], v[0:3], off
	s_nop 0
	s_waitcnt lgkmcnt(7)
	v_cvt_pk_bf16_f32 v0, v142, v143
	ds_read2_b32 v[142:143], v76 offset0:32 offset1:97
	s_waitcnt lgkmcnt(7)
	v_cvt_pk_bf16_f32 v1, v144, v145
	ds_read2_b32 v[144:145], v76 offset0:162 offset1:227
	s_waitcnt lgkmcnt(7)
	v_cvt_pk_bf16_f32 v2, v146, v147
	ds_read2_b32 v[146:147], v10 offset0:36 offset1:101
	s_waitcnt lgkmcnt(7)
	v_cvt_pk_bf16_f32 v3, v148, v149
	ds_read2_b32 v[148:149], v10 offset0:166 offset1:231
	v_or_b32_e32 v4, s16, v78
	v_ashrrev_i32_e32 v5, 31, v4
	v_lshlrev_b64 v[4:5], 12, v[4:5]
	v_lshl_add_u64 v[4:5], v[6:7], 0, v[4:5]
	global_store_dwordx4 v[4:5], v[0:3], off
	s_nop 0
	s_waitcnt lgkmcnt(7)
	v_cvt_pk_bf16_f32 v0, v150, v151
	ds_read2_b32 v[150:151], v76 offset0:40 offset1:105
	s_waitcnt lgkmcnt(7)
	v_cvt_pk_bf16_f32 v1, v152, v153
	ds_read2_b32 v[152:153], v76 offset0:170 offset1:235
	s_waitcnt lgkmcnt(7)
	v_cvt_pk_bf16_f32 v2, v154, v155
	ds_read2_b32 v[154:155], v10 offset0:44 offset1:109
	s_waitcnt lgkmcnt(7)
	v_cvt_pk_bf16_f32 v3, v156, v157
	ds_read2_b32 v[156:157], v10 offset0:174 offset1:239
	v_or_b32_e32 v4, s16, v79
	v_ashrrev_i32_e32 v5, 31, v4
	v_lshlrev_b64 v[4:5], 12, v[4:5]
	v_lshl_add_u64 v[4:5], v[6:7], 0, v[4:5]
	global_store_dwordx4 v[4:5], v[0:3], off
	s_nop 0
	s_waitcnt lgkmcnt(7)
	v_cvt_pk_bf16_f32 v0, v142, v143
	ds_read2_b32 v[142:143], v76 offset0:48 offset1:113
	s_waitcnt lgkmcnt(7)
	v_cvt_pk_bf16_f32 v1, v144, v145
	ds_read2_b32 v[144:145], v76 offset0:178 offset1:243
	s_waitcnt lgkmcnt(7)
	v_cvt_pk_bf16_f32 v2, v146, v147
	ds_read2_b32 v[146:147], v10 offset0:52 offset1:117
	s_waitcnt lgkmcnt(7)
	v_cvt_pk_bf16_f32 v3, v148, v149
	ds_read2_b32 v[148:149], v10 offset0:182 offset1:247
	v_or_b32_e32 v4, s16, v80
	v_ashrrev_i32_e32 v5, 31, v4
	v_lshlrev_b64 v[4:5], 12, v[4:5]
	v_lshl_add_u64 v[4:5], v[6:7], 0, v[4:5]
	global_store_dwordx4 v[4:5], v[0:3], off
	s_nop 0
	s_waitcnt lgkmcnt(7)
	v_cvt_pk_bf16_f32 v0, v150, v151
	ds_read2_b32 v[150:151], v76 offset0:56 offset1:121
	s_waitcnt lgkmcnt(7)
	v_cvt_pk_bf16_f32 v1, v152, v153
	ds_read2_b32 v[152:153], v76 offset0:186 offset1:251
	s_waitcnt lgkmcnt(7)
	v_cvt_pk_bf16_f32 v2, v154, v155
	ds_read2_b32 v[154:155], v10 offset0:60 offset1:125
	s_waitcnt lgkmcnt(7)
	v_cvt_pk_bf16_f32 v3, v156, v157
	ds_read2_b32 v[156:157], v10 offset0:190 offset1:255
	v_or_b32_e32 v4, s16, v81
	v_ashrrev_i32_e32 v5, 31, v4
	v_lshlrev_b64 v[4:5], 12, v[4:5]
	v_lshl_add_u64 v[4:5], v[6:7], 0, v[4:5]
	global_store_dwordx4 v[4:5], v[0:3], off
	s_nop 0
	s_waitcnt lgkmcnt(7)
	v_cvt_pk_bf16_f32 v0, v142, v143
	s_waitcnt lgkmcnt(6)
	v_cvt_pk_bf16_f32 v1, v144, v145
	s_waitcnt lgkmcnt(5)
	v_cvt_pk_bf16_f32 v2, v146, v147
	s_waitcnt lgkmcnt(4)
	v_cvt_pk_bf16_f32 v3, v148, v149
	v_or_b32_e32 v4, s16, v82
	v_ashrrev_i32_e32 v5, 31, v4
	v_lshlrev_b64 v[4:5], 12, v[4:5]
	v_lshl_add_u64 v[4:5], v[6:7], 0, v[4:5]
	global_store_dwordx4 v[4:5], v[0:3], off
	s_nop 0
	s_waitcnt lgkmcnt(3)
	v_cvt_pk_bf16_f32 v0, v150, v151
	s_waitcnt lgkmcnt(2)
	v_cvt_pk_bf16_f32 v1, v152, v153
	s_waitcnt lgkmcnt(1)
	v_cvt_pk_bf16_f32 v2, v154, v155
	s_waitcnt lgkmcnt(0)
	v_cvt_pk_bf16_f32 v3, v156, v157
	v_or_b32_e32 v4, s16, v83
	v_ashrrev_i32_e32 v5, 31, v4
	v_lshlrev_b64 v[4:5], 12, v[4:5]
	v_lshl_add_u64 v[4:5], v[6:7], 0, v[4:5]
	global_store_dwordx4 v[4:5], v[0:3], off
	s_waitcnt lgkmcnt(0)
	s_branch .LBB0_32

; #define LAS __attribute__((address_space(3)))
; __device__ __forceinline__ unsigned cvt_pk_bf16(float lo, float hi) { unsigned r; asm volatile("v_cvt_pk_bf16_f32 %0, %1, %2" : "=v"(r) : "v"(lo), "v"(hi)); return r; }
; template <bool UPPERM> __device__ __forceinline__ void p0_transpose_item(const float* W, int K, int N, bf16_t* WT, const float* gk, LAS float* scr, int item, int lane) {
;     ...
;     const int dn0 = !UPPERM ? n0 : (n0 < FF ? ((n0 >> 7) * 256 + 2 * (n0 & 127)) : ((((n0 - FF) >> 7) * 256) + 2 * ((n0 - FF) & 127) + 32));
;     const int r4 = lane >> 4, c4 = (lane & 15) * 4;
;     f32x4 v[16];
; #pragma unroll
;     for (int i = 0; i < 16; ++i) v[i] = *(const f32x4*)(W + (size_t)(k0 + 4 * i + r4) * N + n0 + c4);
;     if (gk) {
; #pragma unroll
;         for (int i = 0; i < 16; ++i) v[i] *= gk[k0 + 4 * i + r4];
;     }
; #pragma unroll
;     for (int i = 0; i < 16; ++i) { LAS float* d = scr + (4 * i + r4) * 65 + c4; d[0] = v[i][0]; d[1] = v[i][1]; d[2] = v[i][2]; d[3] = v[i][3]; }
;     asm volatile("s_waitcnt lgkmcnt(0)" ::: "memory");
;     const int c = lane & 7;
; #pragma unroll
;     for (int j = 0; j < 8; ++j) { const int n = (lane >> 3) + 8 * j; const LAS float* s = scr + (8 * c) * 65 + n;
;         u32x4 o; o.x = cvt_pk_bf16(s[0 * 65], s[1 * 65]); o.y = cvt_pk_bf16(s[2 * 65], s[3 * 65]); o.z = cvt_pk_bf16(s[4 * 65], s[5 * 65]); o.w = cvt_pk_bf16(s[6 * 65], s[7 * 65]);
;         *(u32x4*)(WT + (size_t)(dn0 + (UPPERM ? ((n >> 5) * 64 + (n & 31)) : n)) * K + k0 + 8 * c) = o; }
.LBB0_361:
	v_add_u32_e32 v0, v69, v76
	s_waitcnt vmcnt(0)
	ds_write2_b32 v0, v6, v7 offset1:1
	ds_write2_b32 v0, v8, v9 offset0:2 offset1:3
	v_add_u32_e32 v6, 0x410, v0
	ds_write2_b32 v6, v2, v3 offset1:1
	v_add_u32_e32 v2, 0x418, v0
	ds_write2_b32 v2, v4, v5 offset1:1
	v_add_u32_e32 v2, 0x820, v0
	ds_write2_b32 v2, v14, v15 offset1:1
	v_add_u32_e32 v2, 0x828, v0
	ds_write2_b32 v2, v16, v17 offset1:1
	v_add_u32_e32 v2, 0xc30, v0
	ds_write2_b32 v2, v10, v11 offset1:1
	v_add_u32_e32 v2, 0xc38, v0
	ds_write2_b32 v2, v12, v13 offset1:1
	v_add_u32_e32 v2, 0x1040, v0
	ds_write2_b32 v2, v22, v23 offset1:1
	v_add_u32_e32 v2, 0x1048, v0
	ds_write2_b32 v2, v24, v25 offset1:1
	v_add_u32_e32 v2, 0x1450, v0
	ds_write2_b32 v2, v18, v19 offset1:1
	v_add_u32_e32 v2, 0x1458, v0
	ds_write2_b32 v2, v20, v21 offset1:1
	v_add_u32_e32 v2, 0x1860, v0
	ds_write2_b32 v2, v30, v31 offset1:1
	v_add_u32_e32 v2, 0x1868, v0
	ds_write2_b32 v2, v32, v33 offset1:1
	v_add_u32_e32 v2, 0x1c70, v0
	ds_write2_b32 v2, v26, v27 offset1:1
	v_add_u32_e32 v2, 0x1c78, v0
	ds_write2_b32 v2, v28, v29 offset1:1
	v_add_u32_e32 v2, 0x2080, v0
	ds_write2_b32 v2, v38, v39 offset1:1
	v_add_u32_e32 v2, 0x2088, v0
	ds_write2_b32 v2, v40, v41 offset1:1
	v_add_u32_e32 v2, 0x2490, v0
	ds_write2_b32 v2, v34, v35 offset1:1
	v_add_u32_e32 v2, 0x2498, v0
	ds_write2_b32 v2, v36, v37 offset1:1
	v_add_u32_e32 v2, 0x28a0, v0
	ds_write2_b32 v2, v46, v47 offset1:1
	v_add_u32_e32 v2, 0x28a8, v0
	ds_write2_b32 v2, v48, v49 offset1:1
	v_add_u32_e32 v2, 0x2cb0, v0
	ds_write2_b32 v2, v42, v43 offset1:1
	v_add_u32_e32 v2, 0x2cb8, v0
	ds_write2_b32 v2, v44, v45 offset1:1
	v_add_u32_e32 v2, 0x30c0, v0
	ds_write2_b32 v2, v54, v55 offset1:1
	v_add_u32_e32 v2, 0x30c8, v0
	ds_write2_b32 v2, v56, v57 offset1:1
	v_add_u32_e32 v2, 0x34d0, v0
	s_lshl_b32 s17, s41, 7
	ds_write2_b32 v2, v50, v51 offset1:1
	v_add_u32_e32 v2, 0x34d8, v0
	s_add_i32 s18, s17, 0x7fffd500
	ds_write2_b32 v2, v52, v53 offset1:1
	v_add_u32_e32 v2, 0x38e0, v0
	s_and_b32 s18, s18, 0x7fffff00
	s_and_b32 s19, s17, 0x80
	ds_write2_b32 v2, v62, v63 offset1:1
	v_add_u32_e32 v2, 0x38e8, v0
	s_or_b32 s18, s19, s18
	ds_write2_b32 v2, v64, v65 offset1:1
	v_add_u32_e32 v2, 0x3cf0, v0
	v_add_u32_e32 v0, 0x3cf8, v0
	s_or_b32 s18, s18, 32
	ds_write2_b32 v2, v58, v59 offset1:1
	ds_write2_b32 v0, v60, v61 offset1:1
	s_cmpk_lt_i32 s41, 0x56
	s_waitcnt lgkmcnt(0)
	s_cselect_b32 s18, s17, s18
	s_ashr_i32 s17, s16, 31
	v_add_u32_e32 v12, 0x400, v78
	ds_read2_b32 v[142:143], v78 offset1:65
	ds_read2_b32 v[144:145], v78 offset0:130 offset1:195
	ds_read2_b32 v[146:147], v12 offset0:4 offset1:69
	ds_read2_b32 v[148:149], v12 offset0:134 offset1:199
	ds_read2_b32 v[150:151], v78 offset0:8 offset1:73
	ds_read2_b32 v[152:153], v78 offset0:138 offset1:203
	ds_read2_b32 v[154:155], v12 offset0:12 offset1:77
	ds_read2_b32 v[156:157], v12 offset0:142 offset1:207
	s_lshl_b64 s[16:17], s[16:17], 1
	s_waitcnt lgkmcnt(7)
	v_cvt_pk_bf16_f32 v2, v142, v143
	ds_read2_b32 v[142:143], v78 offset0:16 offset1:81
	s_add_u32 s12, s12, s16
	s_waitcnt lgkmcnt(7)
	v_cvt_pk_bf16_f32 v3, v144, v145
	ds_read2_b32 v[144:145], v78 offset0:146 offset1:211
	s_addc_u32 s13, s13, s17
	v_lshlrev_b32_e32 v0, 1, v68
	s_waitcnt lgkmcnt(7)
	v_cvt_pk_bf16_f32 v4, v146, v147
	ds_read2_b32 v[146:147], v12 offset0:20 offset1:85
	v_lshl_add_u64 v[8:9], s[12:13], 0, v[0:1]
	v_or_b32_e32 v0, s18, v77
	s_waitcnt lgkmcnt(7)
	v_cvt_pk_bf16_f32 v5, v148, v149
	ds_read2_b32 v[148:149], v12 offset0:150 offset1:215
	v_mad_u64_u32 v[6:7], s[12:13], s0, v0, 0
	s_ashr_i32 s12, s18, 31
	v_mul_lo_u32 v13, s1, v0
	s_mul_i32 s12, s0, s12
	v_add3_u32 v7, v7, s12, v13
	v_lshl_add_u64 v[6:7], v[6:7], 1, v[8:9]
	v_or_b32_e32 v0, s18, v79
	global_store_dwordx4 v[6:7], v[2:5], off
	v_mul_lo_u32 v13, s1, v0
	s_or_b32 s13, s18, 64
	s_waitcnt lgkmcnt(7)
	v_cvt_pk_bf16_f32 v2, v150, v151
	ds_read2_b32 v[150:151], v78 offset0:24 offset1:89
	v_mad_u64_u32 v[10:11], s[16:17], s0, v0, 0
	s_waitcnt lgkmcnt(7)
; #define LAS __attribute__((address_space(3)))
; __device__ __forceinline__ unsigned cvt_pk_bf16(float lo, float hi) { unsigned r; asm volatile("v_cvt_pk_bf16_f32 %0, %1, %2" : "=v"(r) : "v"(lo), "v"(hi)); return r; }
; template <bool UPPERM> __device__ __forceinline__ void p0_transpose_item(const float* W, int K, int N, bf16_t* WT, const float* gk, LAS float* scr, int item, int lane) {
;     ...
;     for (int j = 0; j < 8; ++j) { const int n = (lane >> 3) + 8 * j; const LAS float* s = scr + (8 * c) * 65 + n;
;         u32x4 o; o.x = cvt_pk_bf16(s[0 * 65], s[1 * 65]); o.y = cvt_pk_bf16(s[2 * 65], s[3 * 65]); o.z = cvt_pk_bf16(s[4 * 65], s[5 * 65]); o.w = cvt_pk_bf16(s[6 * 65], s[7 * 65]);
;         *(u32x4*)(WT + (size_t)(dn0 + (UPPERM ? ((n >> 5) * 64 + (n & 31)) : n)) * K + k0 + 8 * c) = o; }
;     asm volatile("s_waitcnt lgkmcnt(0)" ::: "memory");
	v_cvt_pk_bf16_f32 v3, v152, v153
	ds_read2_b32 v[152:153], v78 offset0:154 offset1:219
	v_add3_u32 v11, v11, s12, v13
	s_waitcnt lgkmcnt(7)
	v_cvt_pk_bf16_f32 v4, v154, v155
	ds_read2_b32 v[154:155], v12 offset0:28 offset1:93
	s_waitcnt lgkmcnt(7)
	v_cvt_pk_bf16_f32 v5, v156, v157
	ds_read2_b32 v[156:157], v12 offset0:158 offset1:223
	v_lshl_add_u64 v[10:11], v[10:11], 1, v[8:9]
	v_or_b32_e32 v0, s18, v80
	global_store_dwordx4 v[10:11], v[2:5], off
	v_mul_lo_u32 v13, s1, v0
	v_mad_u64_u32 v[10:11], s[16:17], s0, v0, 0
	s_waitcnt lgkmcnt(7)
	v_cvt_pk_bf16_f32 v2, v142, v143
	ds_read2_b32 v[142:143], v78 offset0:32 offset1:97
	s_waitcnt lgkmcnt(7)
	v_cvt_pk_bf16_f32 v3, v144, v145
	ds_read2_b32 v[144:145], v78 offset0:162 offset1:227
	v_add3_u32 v11, v11, s12, v13
	s_waitcnt lgkmcnt(7)
	v_cvt_pk_bf16_f32 v4, v146, v147
	ds_read2_b32 v[146:147], v12 offset0:36 offset1:101
	s_waitcnt lgkmcnt(7)
	v_cvt_pk_bf16_f32 v5, v148, v149
	ds_read2_b32 v[148:149], v12 offset0:166 offset1:231
	v_lshl_add_u64 v[10:11], v[10:11], 1, v[8:9]
	v_or_b32_e32 v0, s18, v81
	global_store_dwordx4 v[10:11], v[2:5], off
	v_mul_lo_u32 v13, s1, v0
	v_mad_u64_u32 v[10:11], s[16:17], s0, v0, 0
	s_waitcnt lgkmcnt(7)
	v_cvt_pk_bf16_f32 v2, v150, v151
	ds_read2_b32 v[150:151], v78 offset0:40 offset1:105
	s_waitcnt lgkmcnt(7)
	v_cvt_pk_bf16_f32 v3, v152, v153
	ds_read2_b32 v[152:153], v78 offset0:170 offset1:235
	v_add3_u32 v11, v11, s12, v13
	s_waitcnt lgkmcnt(7)
	v_cvt_pk_bf16_f32 v4, v154, v155
	ds_read2_b32 v[154:155], v12 offset0:44 offset1:109
	s_waitcnt lgkmcnt(7)
	v_cvt_pk_bf16_f32 v5, v156, v157
	ds_read2_b32 v[156:157], v12 offset0:174 offset1:239
	v_lshl_add_u64 v[10:11], v[10:11], 1, v[8:9]
	v_or_b32_e32 v0, s13, v77
	global_store_dwordx4 v[10:11], v[2:5], off
	v_mul_lo_u32 v13, s1, v0
	v_mad_u64_u32 v[10:11], s[16:17], s0, v0, 0
	s_waitcnt lgkmcnt(7)
	v_cvt_pk_bf16_f32 v2, v142, v143
	ds_read2_b32 v[142:143], v78 offset0:48 offset1:113
	s_waitcnt lgkmcnt(7)
	v_cvt_pk_bf16_f32 v3, v144, v145
	ds_read2_b32 v[144:145], v78 offset0:178 offset1:243
	v_add3_u32 v11, v11, s12, v13
	s_waitcnt lgkmcnt(7)
	v_cvt_pk_bf16_f32 v4, v146, v147
	ds_read2_b32 v[146:147], v12 offset0:52 offset1:117
	s_waitcnt lgkmcnt(7)
	v_cvt_pk_bf16_f32 v5, v148, v149
	ds_read2_b32 v[148:149], v12 offset0:182 offset1:247
	v_lshl_add_u64 v[10:11], v[10:11], 1, v[8:9]
	v_or_b32_e32 v0, s13, v86
	global_store_dwordx4 v[10:11], v[2:5], off
	v_mul_lo_u32 v13, s1, v0
	v_mad_u64_u32 v[10:11], s[16:17], s0, v0, 0
	s_waitcnt lgkmcnt(7)
	v_cvt_pk_bf16_f32 v2, v150, v151
	ds_read2_b32 v[150:151], v78 offset0:56 offset1:121
	s_waitcnt lgkmcnt(7)
	v_cvt_pk_bf16_f32 v3, v152, v153
	ds_read2_b32 v[152:153], v78 offset0:186 offset1:251
	v_add3_u32 v11, v11, s12, v13
	s_waitcnt lgkmcnt(7)
	v_cvt_pk_bf16_f32 v4, v154, v155
	ds_read2_b32 v[154:155], v12 offset0:60 offset1:125
	s_waitcnt lgkmcnt(7)
	v_cvt_pk_bf16_f32 v5, v156, v157
	ds_read2_b32 v[156:157], v12 offset0:190 offset1:255
	v_lshl_add_u64 v[10:11], v[10:11], 1, v[8:9]
	v_or_b32_e32 v0, s13, v87
	global_store_dwordx4 v[10:11], v[2:5], off
	v_mul_lo_u32 v13, s1, v0
	v_mad_u64_u32 v[10:11], s[16:17], s0, v0, 0
	s_waitcnt lgkmcnt(7)
	v_cvt_pk_bf16_f32 v2, v142, v143
	s_waitcnt lgkmcnt(6)
	v_cvt_pk_bf16_f32 v3, v144, v145
	v_add3_u32 v11, v11, s12, v13
	s_waitcnt lgkmcnt(5)
	v_cvt_pk_bf16_f32 v4, v146, v147
	s_waitcnt lgkmcnt(4)
	v_cvt_pk_bf16_f32 v5, v148, v149
	v_lshl_add_u64 v[10:11], v[10:11], 1, v[8:9]
	global_store_dwordx4 v[10:11], v[2:5], off
	v_or_b32_e32 v0, s13, v88
	v_mul_lo_u32 v10, s1, v0
	s_waitcnt lgkmcnt(3)
	v_cvt_pk_bf16_f32 v2, v150, v151
	s_waitcnt lgkmcnt(2)
	v_cvt_pk_bf16_f32 v3, v152, v153
	s_waitcnt lgkmcnt(1)
	v_cvt_pk_bf16_f32 v4, v154, v155
	s_waitcnt lgkmcnt(0)
	v_cvt_pk_bf16_f32 v5, v156, v157
	v_mad_u64_u32 v[6:7], s[0:1], s0, v0, 0
	v_add3_u32 v7, v7, s12, v10
	v_lshl_add_u64 v[6:7], v[6:7], 1, v[8:9]
	global_store_dwordx4 v[6:7], v[2:5], off
	s_waitcnt lgkmcnt(0)

; #define LAS __attribute__((address_space(3)))
; __device__ __forceinline__ unsigned cvt_pk_bf16(float lo, float hi) { unsigned r; asm volatile("v_cvt_pk_bf16_f32 %0, %1, %2" : "=v"(r) : "v"(lo), "v"(hi)); return r; }
; template <bool UPPERM> __device__ __forceinline__ void p0_transpose_item(const float* W, int K, int N, bf16_t* WT, const float* gk, LAS float* scr, int item, int lane) {
;     ...
;     for (int i = 0; i < 16; ++i) { LAS float* d = scr + (4 * i + r4) * 65 + c4; d[0] = v[i][0]; d[1] = v[i][1]; d[2] = v[i][2]; d[3] = v[i][3]; }
;     asm volatile("s_waitcnt lgkmcnt(0)" ::: "memory");
;     const int c = lane & 7;
; #pragma unroll
;     for (int j = 0; j < 8; ++j) { const int n = (lane >> 3) + 8 * j; const LAS float* s = scr + (8 * c) * 65 + n;
;         u32x4 o; o.x = cvt_pk_bf16(s[0 * 65], s[1 * 65]); o.y = cvt_pk_bf16(s[2 * 65], s[3 * 65]); o.z = cvt_pk_bf16(s[4 * 65], s[5 * 65]); o.w = cvt_pk_bf16(s[6 * 65], s[7 * 65]);
;         *(u32x4*)(WT + (size_t)(dn0 + (UPPERM ? ((n >> 5) * 64 + (n & 31)) : n)) * K + k0 + 8 * c) = o; }
.LBB0_384:
	v_add_u32_e32 v71, v69, v76
	s_waitcnt vmcnt(0)
	ds_write2_b32 v71, v6, v7 offset1:1
	ds_write2_b32 v71, v8, v9 offset0:2 offset1:3
	v_add_u32_e32 v6, 0x410, v71
	ds_write2_b32 v6, v2, v3 offset1:1
	v_add_u32_e32 v2, 0x418, v71
	ds_write2_b32 v2, v4, v5 offset1:1
	v_add_u32_e32 v2, 0x820, v71
	ds_write2_b32 v2, v14, v15 offset1:1
	v_add_u32_e32 v2, 0x828, v71
	ds_write2_b32 v2, v16, v17 offset1:1
	v_add_u32_e32 v2, 0xc30, v71
	ds_write2_b32 v2, v10, v11 offset1:1
	v_add_u32_e32 v2, 0xc38, v71
	ds_write2_b32 v2, v12, v13 offset1:1
	v_add_u32_e32 v2, 0x1040, v71
	ds_write2_b32 v2, v22, v23 offset1:1
	v_add_u32_e32 v2, 0x1048, v71
	ds_write2_b32 v2, v24, v25 offset1:1
	v_add_u32_e32 v2, 0x1450, v71
	ds_write2_b32 v2, v18, v19 offset1:1
	v_add_u32_e32 v2, 0x1458, v71
	ds_write2_b32 v2, v20, v21 offset1:1
	v_add_u32_e32 v2, 0x1860, v71
	ds_write2_b32 v2, v30, v31 offset1:1
	v_add_u32_e32 v2, 0x1868, v71
	ds_write2_b32 v2, v32, v33 offset1:1
	v_add_u32_e32 v2, 0x1c70, v71
	ds_write2_b32 v2, v26, v27 offset1:1
	v_add_u32_e32 v2, 0x1c78, v71
	ds_write2_b32 v2, v28, v29 offset1:1
	v_add_u32_e32 v2, 0x2080, v71
	ds_write2_b32 v2, v38, v39 offset1:1
	v_add_u32_e32 v2, 0x2088, v71
	ds_write2_b32 v2, v40, v41 offset1:1
	v_add_u32_e32 v2, 0x2490, v71
	ds_write2_b32 v2, v34, v35 offset1:1
	v_add_u32_e32 v2, 0x2498, v71
	ds_write2_b32 v2, v36, v37 offset1:1
	v_add_u32_e32 v2, 0x28a0, v71
	ds_write2_b32 v2, v46, v47 offset1:1
	v_add_u32_e32 v2, 0x28a8, v71
	ds_write2_b32 v2, v48, v49 offset1:1
	v_add_u32_e32 v2, 0x2cb0, v71
	ds_write2_b32 v2, v42, v43 offset1:1
	v_add_u32_e32 v2, 0x2cb8, v71
	ds_write2_b32 v2, v44, v45 offset1:1
	v_add_u32_e32 v2, 0x30c0, v71
	ds_write2_b32 v2, v54, v55 offset1:1
	v_add_u32_e32 v2, 0x30c8, v71
	ds_write2_b32 v2, v56, v57 offset1:1
	v_add_u32_e32 v2, 0x34d0, v71
	ds_write2_b32 v2, v50, v51 offset1:1
	v_add_u32_e32 v2, 0x34d8, v71
	ds_write2_b32 v2, v52, v53 offset1:1
	v_add_u32_e32 v2, 0x38e0, v71
	ds_write2_b32 v2, v62, v63 offset1:1
	v_add_u32_e32 v2, 0x38e8, v71
	ds_write2_b32 v2, v64, v65 offset1:1
	v_add_u32_e32 v2, 0x3cf0, v71
	ds_write2_b32 v2, v58, v59 offset1:1
	v_add_u32_e32 v2, 0x3cf8, v71
	ds_write2_b32 v2, v60, v61 offset1:1
	s_ashr_i32 s17, s16, 31
	s_waitcnt lgkmcnt(0)
	s_lshl_b64 s[36:37], s[16:17], 1
	v_add_u32_e32 v12, 0x400, v78
	ds_read2_b32 v[142:143], v78 offset1:65
	ds_read2_b32 v[144:145], v78 offset0:130 offset1:195
	ds_read2_b32 v[146:147], v12 offset0:4 offset1:69
	ds_read2_b32 v[148:149], v12 offset0:134 offset1:199
	ds_read2_b32 v[150:151], v78 offset0:8 offset1:73
	ds_read2_b32 v[152:153], v78 offset0:138 offset1:203
	ds_read2_b32 v[154:155], v12 offset0:12 offset1:77
	ds_read2_b32 v[156:157], v12 offset0:142 offset1:207
	s_add_u32 s36, s12, s36
	s_waitcnt lgkmcnt(7)
	v_cvt_pk_bf16_f32 v2, v142, v143
	ds_read2_b32 v[142:143], v78 offset0:16 offset1:81
	s_addc_u32 s37, s13, s37
	v_lshlrev_b32_e32 v8, 1, v68
	v_mov_b32_e32 v9, v1
	v_or_b32_e32 v10, s34, v77
	s_waitcnt lgkmcnt(7)
	v_cvt_pk_bf16_f32 v3, v144, v145
	ds_read2_b32 v[144:145], v78 offset0:146 offset1:211
	v_lshl_add_u64 v[8:9], s[36:37], 0, v[8:9]
	v_mul_hi_i32_i24_e32 v11, s0, v10
	v_mul_i32_i24_e32 v10, s0, v10
	s_waitcnt lgkmcnt(7)
	v_cvt_pk_bf16_f32 v4, v146, v147
	ds_read2_b32 v[146:147], v12 offset0:20 offset1:85
	s_waitcnt lgkmcnt(7)
	v_cvt_pk_bf16_f32 v5, v148, v149
	ds_read2_b32 v[148:149], v12 offset0:150 offset1:215
	v_lshl_add_u64 v[10:11], v[10:11], 1, v[8:9]
	global_store_dwordx4 v[10:11], v[2:5], off
	v_or_b32_e32 v10, s34, v79
	v_mul_hi_i32_i24_e32 v11, s0, v10
	s_waitcnt lgkmcnt(7)
	v_cvt_pk_bf16_f32 v2, v150, v151
	ds_read2_b32 v[150:151], v78 offset0:24 offset1:89
	s_waitcnt lgkmcnt(7)
; #define LAS __attribute__((address_space(3)))
; __device__ __forceinline__ unsigned cvt_pk_bf16(float lo, float hi) { unsigned r; asm volatile("v_cvt_pk_bf16_f32 %0, %1, %2" : "=v"(r) : "v"(lo), "v"(hi)); return r; }
; template <bool UPPERM> __device__ __forceinline__ void p0_transpose_item(const float* W, int K, int N, bf16_t* WT, const float* gk, LAS float* scr, int item, int lane) {
;     ...
;     for (int j = 0; j < 8; ++j) { const int n = (lane >> 3) + 8 * j; const LAS float* s = scr + (8 * c) * 65 + n;
;         u32x4 o; o.x = cvt_pk_bf16(s[0 * 65], s[1 * 65]); o.y = cvt_pk_bf16(s[2 * 65], s[3 * 65]); o.z = cvt_pk_bf16(s[4 * 65], s[5 * 65]); o.w = cvt_pk_bf16(s[6 * 65], s[7 * 65]);
;         *(u32x4*)(WT + (size_t)(dn0 + (UPPERM ? ((n >> 5) * 64 + (n & 31)) : n)) * K + k0 + 8 * c) = o; }
;     asm volatile("s_waitcnt lgkmcnt(0)" ::: "memory");
	v_cvt_pk_bf16_f32 v3, v152, v153
	ds_read2_b32 v[152:153], v78 offset0:154 offset1:219
	v_mul_i32_i24_e32 v10, s0, v10
	s_waitcnt lgkmcnt(7)
	v_cvt_pk_bf16_f32 v4, v154, v155
	ds_read2_b32 v[154:155], v12 offset0:28 offset1:93
	s_waitcnt lgkmcnt(7)
	v_cvt_pk_bf16_f32 v5, v156, v157
	ds_read2_b32 v[156:157], v12 offset0:158 offset1:223
	v_lshl_add_u64 v[10:11], v[10:11], 1, v[8:9]
	global_store_dwordx4 v[10:11], v[2:5], off
	v_or_b32_e32 v10, s34, v80
	v_mul_hi_i32_i24_e32 v11, s0, v10
	s_waitcnt lgkmcnt(7)
	v_cvt_pk_bf16_f32 v2, v142, v143
	ds_read2_b32 v[142:143], v78 offset0:32 offset1:97
	s_waitcnt lgkmcnt(7)
	v_cvt_pk_bf16_f32 v3, v144, v145
	ds_read2_b32 v[144:145], v78 offset0:162 offset1:227
	v_mul_i32_i24_e32 v10, s0, v10
	s_waitcnt lgkmcnt(7)
	v_cvt_pk_bf16_f32 v4, v146, v147
	ds_read2_b32 v[146:147], v12 offset0:36 offset1:101
	s_waitcnt lgkmcnt(7)
	v_cvt_pk_bf16_f32 v5, v148, v149
	ds_read2_b32 v[148:149], v12 offset0:166 offset1:231
	v_lshl_add_u64 v[10:11], v[10:11], 1, v[8:9]
	global_store_dwordx4 v[10:11], v[2:5], off
	v_or_b32_e32 v10, s34, v81
	v_mul_hi_i32_i24_e32 v11, s0, v10
	s_waitcnt lgkmcnt(7)
	v_cvt_pk_bf16_f32 v2, v150, v151
	ds_read2_b32 v[150:151], v78 offset0:40 offset1:105
	s_waitcnt lgkmcnt(7)
	v_cvt_pk_bf16_f32 v3, v152, v153
	ds_read2_b32 v[152:153], v78 offset0:170 offset1:235
	v_mul_i32_i24_e32 v10, s0, v10
	s_waitcnt lgkmcnt(7)
	v_cvt_pk_bf16_f32 v4, v154, v155
	ds_read2_b32 v[154:155], v12 offset0:44 offset1:109
	s_waitcnt lgkmcnt(7)
	v_cvt_pk_bf16_f32 v5, v156, v157
	ds_read2_b32 v[156:157], v12 offset0:174 offset1:239
	v_lshl_add_u64 v[10:11], v[10:11], 1, v[8:9]
	global_store_dwordx4 v[10:11], v[2:5], off
	v_or_b32_e32 v10, s34, v82
	v_mul_hi_i32_i24_e32 v11, s0, v10
	s_waitcnt lgkmcnt(7)
	v_cvt_pk_bf16_f32 v2, v142, v143
	ds_read2_b32 v[142:143], v78 offset0:48 offset1:113
	s_waitcnt lgkmcnt(7)
	v_cvt_pk_bf16_f32 v3, v144, v145
	ds_read2_b32 v[144:145], v78 offset0:178 offset1:243
	v_mul_i32_i24_e32 v10, s0, v10
	s_waitcnt lgkmcnt(7)
	v_cvt_pk_bf16_f32 v4, v146, v147
	ds_read2_b32 v[146:147], v12 offset0:52 offset1:117
	s_waitcnt lgkmcnt(7)
	v_cvt_pk_bf16_f32 v5, v148, v149
	ds_read2_b32 v[148:149], v12 offset0:182 offset1:247
	v_lshl_add_u64 v[10:11], v[10:11], 1, v[8:9]
	global_store_dwordx4 v[10:11], v[2:5], off
	v_or_b32_e32 v10, s34, v83
	v_mul_hi_i32_i24_e32 v11, s0, v10
	s_waitcnt lgkmcnt(7)
	v_cvt_pk_bf16_f32 v2, v150, v151
	ds_read2_b32 v[150:151], v78 offset0:56 offset1:121
	s_waitcnt lgkmcnt(7)
	v_cvt_pk_bf16_f32 v3, v152, v153
	ds_read2_b32 v[152:153], v78 offset0:186 offset1:251
	v_mul_i32_i24_e32 v10, s0, v10
	s_waitcnt lgkmcnt(7)
	v_cvt_pk_bf16_f32 v4, v154, v155
	ds_read2_b32 v[154:155], v12 offset0:60 offset1:125
	s_waitcnt lgkmcnt(7)
	v_cvt_pk_bf16_f32 v5, v156, v157
	ds_read2_b32 v[156:157], v12 offset0:190 offset1:255
	v_lshl_add_u64 v[10:11], v[10:11], 1, v[8:9]
	global_store_dwordx4 v[10:11], v[2:5], off
	v_or_b32_e32 v10, s34, v84
	v_mul_hi_i32_i24_e32 v11, s0, v10
	s_waitcnt lgkmcnt(7)
	v_cvt_pk_bf16_f32 v2, v142, v143
	s_waitcnt lgkmcnt(6)
	v_cvt_pk_bf16_f32 v3, v144, v145
	v_mul_i32_i24_e32 v10, s0, v10
	s_waitcnt lgkmcnt(5)
	v_cvt_pk_bf16_f32 v4, v146, v147
	s_waitcnt lgkmcnt(4)
	v_cvt_pk_bf16_f32 v5, v148, v149
	v_lshl_add_u64 v[10:11], v[10:11], 1, v[8:9]
	global_store_dwordx4 v[10:11], v[2:5], off
	s_nop 0
	s_waitcnt lgkmcnt(3)
	v_cvt_pk_bf16_f32 v2, v150, v151
	s_waitcnt lgkmcnt(2)
	v_cvt_pk_bf16_f32 v3, v152, v153
	s_waitcnt lgkmcnt(1)
	v_cvt_pk_bf16_f32 v4, v154, v155
	s_waitcnt lgkmcnt(0)
	v_cvt_pk_bf16_f32 v5, v156, v157
	v_or_b32_e32 v6, s34, v85
	v_mul_hi_i32_i24_e32 v7, s0, v6
	v_mul_i32_i24_e32 v6, s0, v6
	v_lshl_add_u64 v[6:7], v[6:7], 1, v[8:9]
	global_store_dwordx4 v[6:7], v[2:5], off
	s_waitcnt lgkmcnt(0)
	s_branch .LBB0_362

; #define LAS __attribute__((address_space(3)))
; __device__ __forceinline__ unsigned cvt_pk_bf16(float lo, float hi) { unsigned r; asm volatile("v_cvt_pk_bf16_f32 %0, %1, %2" : "=v"(r) : "v"(lo), "v"(hi)); return r; }
; template <bool UPPERM> __device__ __forceinline__ void p0_transpose_item(const float* W, int K, int N, bf16_t* WT, const float* gk, LAS float* scr, int item, int lane) {
;     ...
;     const int dn0 = !UPPERM ? n0 : (n0 < FF ? ((n0 >> 7) * 256 + 2 * (n0 & 127)) : ((((n0 - FF) >> 7) * 256) + 2 * ((n0 - FF) & 127) + 32));
;     const int r4 = lane >> 4, c4 = (lane & 15) * 4;
;     f32x4 v[16];
; #pragma unroll
;     for (int i = 0; i < 16; ++i) v[i] = *(const f32x4*)(W + (size_t)(k0 + 4 * i + r4) * N + n0 + c4);
;     if (gk) {
; #pragma unroll
;         for (int i = 0; i < 16; ++i) v[i] *= gk[k0 + 4 * i + r4];
;     }
; #pragma unroll
;     for (int i = 0; i < 16; ++i) { LAS float* d = scr + (4 * i + r4) * 65 + c4; d[0] = v[i][0]; d[1] = v[i][1]; d[2] = v[i][2]; d[3] = v[i][3]; }
;     asm volatile("s_waitcnt lgkmcnt(0)" ::: "memory");
;     const int c = lane & 7;
; #pragma unroll
;     for (int j = 0; j < 8; ++j) { const int n = (lane >> 3) + 8 * j; const LAS float* s = scr + (8 * c) * 65 + n;
;         u32x4 o; o.x = cvt_pk_bf16(s[0 * 65], s[1 * 65]); o.y = cvt_pk_bf16(s[2 * 65], s[3 * 65]); o.z = cvt_pk_bf16(s[4 * 65], s[5 * 65]); o.w = cvt_pk_bf16(s[6 * 65], s[7 * 65]);
;         *(u32x4*)(WT + (size_t)(dn0 + (UPPERM ? ((n >> 5) * 64 + (n & 31)) : n)) * K + k0 + 8 * c) = o; }
.LBB0_794:
	v_add_u32_e32 v0, v69, v76
	s_waitcnt vmcnt(15)
	ds_write2_b32 v0, v6, v7 offset1:1
	ds_write2_b32 v0, v8, v9 offset0:2 offset1:3
	v_add_u32_e32 v6, 0x410, v0
	s_waitcnt vmcnt(14)
	ds_write2_b32 v6, v2, v3 offset1:1
	v_add_u32_e32 v2, 0x418, v0
	ds_write2_b32 v2, v4, v5 offset1:1
	v_add_u32_e32 v2, 0x820, v0
	s_waitcnt vmcnt(13)
	ds_write2_b32 v2, v14, v15 offset1:1
	v_add_u32_e32 v2, 0x828, v0
	ds_write2_b32 v2, v16, v17 offset1:1
	v_add_u32_e32 v2, 0xc30, v0
	s_waitcnt vmcnt(12)
	ds_write2_b32 v2, v10, v11 offset1:1
	v_add_u32_e32 v2, 0xc38, v0
	ds_write2_b32 v2, v12, v13 offset1:1
	v_add_u32_e32 v2, 0x1040, v0
	s_waitcnt vmcnt(11)
	ds_write2_b32 v2, v22, v23 offset1:1
	v_add_u32_e32 v2, 0x1048, v0
	ds_write2_b32 v2, v24, v25 offset1:1
	v_add_u32_e32 v2, 0x1450, v0
	s_waitcnt vmcnt(10)
	ds_write2_b32 v2, v18, v19 offset1:1
	v_add_u32_e32 v2, 0x1458, v0
	ds_write2_b32 v2, v20, v21 offset1:1
	v_add_u32_e32 v2, 0x1860, v0
	s_waitcnt vmcnt(9)
	ds_write2_b32 v2, v30, v31 offset1:1
	v_add_u32_e32 v2, 0x1868, v0
	ds_write2_b32 v2, v32, v33 offset1:1
	v_add_u32_e32 v2, 0x1c70, v0
	s_waitcnt vmcnt(8)
	ds_write2_b32 v2, v26, v27 offset1:1
	v_add_u32_e32 v2, 0x1c78, v0
	ds_write2_b32 v2, v28, v29 offset1:1
	v_add_u32_e32 v2, 0x2080, v0
	s_waitcnt vmcnt(7)
	ds_write2_b32 v2, v38, v39 offset1:1
	v_add_u32_e32 v2, 0x2088, v0
	ds_write2_b32 v2, v40, v41 offset1:1
	v_add_u32_e32 v2, 0x2490, v0
	s_waitcnt vmcnt(6)
	ds_write2_b32 v2, v34, v35 offset1:1
	v_add_u32_e32 v2, 0x2498, v0
	ds_write2_b32 v2, v36, v37 offset1:1
	v_add_u32_e32 v2, 0x28a0, v0
	s_waitcnt vmcnt(5)
	ds_write2_b32 v2, v46, v47 offset1:1
	v_add_u32_e32 v2, 0x28a8, v0
	ds_write2_b32 v2, v48, v49 offset1:1
	v_add_u32_e32 v2, 0x2cb0, v0
	s_waitcnt vmcnt(4)
	ds_write2_b32 v2, v42, v43 offset1:1
	v_add_u32_e32 v2, 0x2cb8, v0
	ds_write2_b32 v2, v44, v45 offset1:1
	v_add_u32_e32 v2, 0x30c0, v0
	s_waitcnt vmcnt(3)
	ds_write2_b32 v2, v54, v55 offset1:1
	v_add_u32_e32 v2, 0x30c8, v0
	ds_write2_b32 v2, v56, v57 offset1:1
	v_add_u32_e32 v2, 0x34d0, v0
	s_lshl_b32 s17, s43, 7
	s_waitcnt vmcnt(2)
	ds_write2_b32 v2, v50, v51 offset1:1
	v_add_u32_e32 v2, 0x34d8, v0
	s_add_i32 s30, s17, 0x7fffd500
	ds_write2_b32 v2, v52, v53 offset1:1
	v_add_u32_e32 v2, 0x38e0, v0
	s_and_b32 s30, s30, 0x7fffff00
	s_and_b32 s31, s17, 0x80
	s_waitcnt vmcnt(1)
	ds_write2_b32 v2, v62, v63 offset1:1
	v_add_u32_e32 v2, 0x38e8, v0
	s_or_b32 s30, s31, s30
	ds_write2_b32 v2, v64, v65 offset1:1
	v_add_u32_e32 v2, 0x3cf0, v0
	v_add_u32_e32 v0, 0x3cf8, v0
	s_or_b32 s30, s30, 32
	s_waitcnt vmcnt(0)
	ds_write2_b32 v2, v58, v59 offset1:1
	ds_write2_b32 v0, v60, v61 offset1:1
	s_cmpk_lt_i32 s43, 0x56
	s_waitcnt lgkmcnt(0)
	s_cselect_b32 s30, s17, s30
	s_ashr_i32 s17, s16, 31
	v_add_u32_e32 v12, 0x400, v78
	ds_read2_b32 v[142:143], v78 offset1:65
	ds_read2_b32 v[144:145], v78 offset0:130 offset1:195
	ds_read2_b32 v[146:147], v12 offset0:4 offset1:69
	ds_read2_b32 v[148:149], v12 offset0:134 offset1:199
	ds_read2_b32 v[150:151], v78 offset0:8 offset1:73
	ds_read2_b32 v[152:153], v78 offset0:138 offset1:203
	ds_read2_b32 v[154:155], v12 offset0:12 offset1:77
	ds_read2_b32 v[156:157], v12 offset0:142 offset1:207
	s_lshl_b64 s[16:17], s[16:17], 1
	s_waitcnt lgkmcnt(7)
	v_cvt_pk_bf16_f32 v2, v142, v143
	ds_read2_b32 v[142:143], v78 offset0:16 offset1:81
	s_add_u32 s12, s12, s16
	s_waitcnt lgkmcnt(7)
	v_cvt_pk_bf16_f32 v3, v144, v145
	ds_read2_b32 v[144:145], v78 offset0:146 offset1:211
	s_addc_u32 s13, s13, s17
	v_lshlrev_b32_e32 v0, 1, v68
	s_waitcnt lgkmcnt(7)
	v_cvt_pk_bf16_f32 v4, v146, v147
	ds_read2_b32 v[146:147], v12 offset0:20 offset1:85
	v_lshl_add_u64 v[8:9], s[12:13], 0, v[0:1]
	v_or_b32_e32 v0, s30, v77
	s_waitcnt lgkmcnt(7)
	v_cvt_pk_bf16_f32 v5, v148, v149
	ds_read2_b32 v[148:149], v12 offset0:150 offset1:215
	v_mad_u64_u32 v[6:7], s[12:13], s0, v0, 0
	s_ashr_i32 s12, s30, 31
	v_mul_lo_u32 v13, s1, v0
	s_mul_i32 s12, s0, s12
	v_add3_u32 v7, v7, s12, v13
	v_lshl_add_u64 v[6:7], v[6:7], 1, v[8:9]
	v_or_b32_e32 v0, s30, v79
	global_store_dwordx4 v[6:7], v[2:5], off
	v_mul_lo_u32 v13, s1, v0
	s_or_b32 s13, s30, 64
	s_waitcnt lgkmcnt(7)
; #define LAS __attribute__((address_space(3)))
; __device__ __forceinline__ unsigned cvt_pk_bf16(float lo, float hi) { unsigned r; asm volatile("v_cvt_pk_bf16_f32 %0, %1, %2" : "=v"(r) : "v"(lo), "v"(hi)); return r; }
; template <bool UPPERM> __device__ __forceinline__ void p0_transpose_item(const float* W, int K, int N, bf16_t* WT, const float* gk, LAS float* scr, int item, int lane) {
;     ...
;     for (int j = 0; j < 8; ++j) { const int n = (lane >> 3) + 8 * j; const LAS float* s = scr + (8 * c) * 65 + n;
;         u32x4 o; o.x = cvt_pk_bf16(s[0 * 65], s[1 * 65]); o.y = cvt_pk_bf16(s[2 * 65], s[3 * 65]); o.z = cvt_pk_bf16(s[4 * 65], s[5 * 65]); o.w = cvt_pk_bf16(s[6 * 65], s[7 * 65]);
;         *(u32x4*)(WT + (size_t)(dn0 + (UPPERM ? ((n >> 5) * 64 + (n & 31)) : n)) * K + k0 + 8 * c) = o; }
;     asm volatile("s_waitcnt lgkmcnt(0)" ::: "memory");
	v_cvt_pk_bf16_f32 v2, v150, v151
	ds_read2_b32 v[150:151], v78 offset0:24 offset1:89
	v_mad_u64_u32 v[10:11], s[16:17], s0, v0, 0
	s_waitcnt lgkmcnt(7)
	v_cvt_pk_bf16_f32 v3, v152, v153
	ds_read2_b32 v[152:153], v78 offset0:154 offset1:219
	v_add3_u32 v11, v11, s12, v13
	s_waitcnt lgkmcnt(7)
	v_cvt_pk_bf16_f32 v4, v154, v155
	ds_read2_b32 v[154:155], v12 offset0:28 offset1:93
	s_waitcnt lgkmcnt(7)
	v_cvt_pk_bf16_f32 v5, v156, v157
	ds_read2_b32 v[156:157], v12 offset0:158 offset1:223
	v_lshl_add_u64 v[10:11], v[10:11], 1, v[8:9]
	v_or_b32_e32 v0, s30, v80
	global_store_dwordx4 v[10:11], v[2:5], off
	v_mul_lo_u32 v13, s1, v0
	v_mad_u64_u32 v[10:11], s[16:17], s0, v0, 0
	s_waitcnt lgkmcnt(7)
	v_cvt_pk_bf16_f32 v2, v142, v143
	ds_read2_b32 v[142:143], v78 offset0:32 offset1:97
	s_waitcnt lgkmcnt(7)
	v_cvt_pk_bf16_f32 v3, v144, v145
	ds_read2_b32 v[144:145], v78 offset0:162 offset1:227
	v_add3_u32 v11, v11, s12, v13
	s_waitcnt lgkmcnt(7)
	v_cvt_pk_bf16_f32 v4, v146, v147
	ds_read2_b32 v[146:147], v12 offset0:36 offset1:101
	s_waitcnt lgkmcnt(7)
	v_cvt_pk_bf16_f32 v5, v148, v149
	ds_read2_b32 v[148:149], v12 offset0:166 offset1:231
	v_lshl_add_u64 v[10:11], v[10:11], 1, v[8:9]
	v_or_b32_e32 v0, s30, v81
	global_store_dwordx4 v[10:11], v[2:5], off
	v_mul_lo_u32 v13, s1, v0
	v_mad_u64_u32 v[10:11], s[16:17], s0, v0, 0
	s_waitcnt lgkmcnt(7)
	v_cvt_pk_bf16_f32 v2, v150, v151
	ds_read2_b32 v[150:151], v78 offset0:40 offset1:105
	s_waitcnt lgkmcnt(7)
	v_cvt_pk_bf16_f32 v3, v152, v153
	ds_read2_b32 v[152:153], v78 offset0:170 offset1:235
	v_add3_u32 v11, v11, s12, v13
	s_waitcnt lgkmcnt(7)
	v_cvt_pk_bf16_f32 v4, v154, v155
	ds_read2_b32 v[154:155], v12 offset0:44 offset1:109
	s_waitcnt lgkmcnt(7)
	v_cvt_pk_bf16_f32 v5, v156, v157
	ds_read2_b32 v[156:157], v12 offset0:174 offset1:239
	v_lshl_add_u64 v[10:11], v[10:11], 1, v[8:9]
	v_or_b32_e32 v0, s13, v77
	global_store_dwordx4 v[10:11], v[2:5], off
	v_mul_lo_u32 v13, s1, v0
	v_mad_u64_u32 v[10:11], s[16:17], s0, v0, 0
	s_waitcnt lgkmcnt(7)
	v_cvt_pk_bf16_f32 v2, v142, v143
	ds_read2_b32 v[142:143], v78 offset0:48 offset1:113
	s_waitcnt lgkmcnt(7)
	v_cvt_pk_bf16_f32 v3, v144, v145
	ds_read2_b32 v[144:145], v78 offset0:178 offset1:243
	v_add3_u32 v11, v11, s12, v13
	s_waitcnt lgkmcnt(7)
	v_cvt_pk_bf16_f32 v4, v146, v147
	ds_read2_b32 v[146:147], v12 offset0:52 offset1:117
	s_waitcnt lgkmcnt(7)
	v_cvt_pk_bf16_f32 v5, v148, v149
	ds_read2_b32 v[148:149], v12 offset0:182 offset1:247
	v_lshl_add_u64 v[10:11], v[10:11], 1, v[8:9]
	v_or_b32_e32 v0, s13, v86
	global_store_dwordx4 v[10:11], v[2:5], off
	v_mul_lo_u32 v13, s1, v0
	v_mad_u64_u32 v[10:11], s[16:17], s0, v0, 0
	s_waitcnt lgkmcnt(7)
	v_cvt_pk_bf16_f32 v2, v150, v151
	ds_read2_b32 v[150:151], v78 offset0:56 offset1:121
	s_waitcnt lgkmcnt(7)
	v_cvt_pk_bf16_f32 v3, v152, v153
	ds_read2_b32 v[152:153], v78 offset0:186 offset1:251
	v_add3_u32 v11, v11, s12, v13
	s_waitcnt lgkmcnt(7)
	v_cvt_pk_bf16_f32 v4, v154, v155
	ds_read2_b32 v[154:155], v12 offset0:60 offset1:125
	s_waitcnt lgkmcnt(7)
	v_cvt_pk_bf16_f32 v5, v156, v157
	ds_read2_b32 v[156:157], v12 offset0:190 offset1:255
	v_lshl_add_u64 v[10:11], v[10:11], 1, v[8:9]
	v_or_b32_e32 v0, s13, v87
	global_store_dwordx4 v[10:11], v[2:5], off
	v_mul_lo_u32 v13, s1, v0
	v_mad_u64_u32 v[10:11], s[16:17], s0, v0, 0
	s_waitcnt lgkmcnt(7)
	v_cvt_pk_bf16_f32 v2, v142, v143
	s_waitcnt lgkmcnt(6)
	v_cvt_pk_bf16_f32 v3, v144, v145
	v_add3_u32 v11, v11, s12, v13
	s_waitcnt lgkmcnt(5)
	v_cvt_pk_bf16_f32 v4, v146, v147
	s_waitcnt lgkmcnt(4)
	v_cvt_pk_bf16_f32 v5, v148, v149
	v_lshl_add_u64 v[10:11], v[10:11], 1, v[8:9]
	global_store_dwordx4 v[10:11], v[2:5], off
	v_or_b32_e32 v0, s13, v88
	v_mul_lo_u32 v10, s1, v0
	s_waitcnt lgkmcnt(3)
	v_cvt_pk_bf16_f32 v2, v150, v151
	s_waitcnt lgkmcnt(2)
	v_cvt_pk_bf16_f32 v3, v152, v153
	s_waitcnt lgkmcnt(1)
	v_cvt_pk_bf16_f32 v4, v154, v155
	s_waitcnt lgkmcnt(0)
	v_cvt_pk_bf16_f32 v5, v156, v157
	v_mad_u64_u32 v[6:7], s[0:1], s0, v0, 0
	v_add3_u32 v7, v7, s12, v10
	v_lshl_add_u64 v[6:7], v[6:7], 1, v[8:9]
	global_store_dwordx4 v[6:7], v[2:5], off
	s_waitcnt lgkmcnt(0)

; #define LAS __attribute__((address_space(3)))
; __device__ __forceinline__ unsigned cvt_pk_bf16(float lo, float hi) { unsigned r; asm volatile("v_cvt_pk_bf16_f32 %0, %1, %2" : "=v"(r) : "v"(lo), "v"(hi)); return r; }
; template <bool UPPERM> __device__ __forceinline__ void p0_transpose_item(const float* W, int K, int N, bf16_t* WT, const float* gk, LAS float* scr, int item, int lane) {
;     ...
;     for (int i = 0; i < 16; ++i) { LAS float* d = scr + (4 * i + r4) * 65 + c4; d[0] = v[i][0]; d[1] = v[i][1]; d[2] = v[i][2]; d[3] = v[i][3]; }
;     asm volatile("s_waitcnt lgkmcnt(0)" ::: "memory");
;     const int c = lane & 7;
; #pragma unroll
;     for (int j = 0; j < 8; ++j) { const int n = (lane >> 3) + 8 * j; const LAS float* s = scr + (8 * c) * 65 + n;
;         u32x4 o; o.x = cvt_pk_bf16(s[0 * 65], s[1 * 65]); o.y = cvt_pk_bf16(s[2 * 65], s[3 * 65]); o.z = cvt_pk_bf16(s[4 * 65], s[5 * 65]); o.w = cvt_pk_bf16(s[6 * 65], s[7 * 65]);
;         *(u32x4*)(WT + (size_t)(dn0 + (UPPERM ? ((n >> 5) * 64 + (n & 31)) : n)) * K + k0 + 8 * c) = o; }
.LBB0_816:
	v_add_u32_e32 v71, v69, v76
	s_waitcnt vmcnt(15)
	ds_write2_b32 v71, v6, v7 offset1:1
	ds_write2_b32 v71, v8, v9 offset0:2 offset1:3
	v_add_u32_e32 v6, 0x410, v71
	s_waitcnt vmcnt(14)
	ds_write2_b32 v6, v2, v3 offset1:1
	v_add_u32_e32 v2, 0x418, v71
	ds_write2_b32 v2, v4, v5 offset1:1
	v_add_u32_e32 v2, 0x820, v71
	s_waitcnt vmcnt(13)
	ds_write2_b32 v2, v14, v15 offset1:1
	v_add_u32_e32 v2, 0x828, v71
	ds_write2_b32 v2, v16, v17 offset1:1
	v_add_u32_e32 v2, 0xc30, v71
	s_waitcnt vmcnt(12)
	ds_write2_b32 v2, v10, v11 offset1:1
	v_add_u32_e32 v2, 0xc38, v71
	ds_write2_b32 v2, v12, v13 offset1:1
	v_add_u32_e32 v2, 0x1040, v71
	s_waitcnt vmcnt(11)
	ds_write2_b32 v2, v22, v23 offset1:1
	v_add_u32_e32 v2, 0x1048, v71
	ds_write2_b32 v2, v24, v25 offset1:1
	v_add_u32_e32 v2, 0x1450, v71
	s_waitcnt vmcnt(10)
	ds_write2_b32 v2, v18, v19 offset1:1
	v_add_u32_e32 v2, 0x1458, v71
	ds_write2_b32 v2, v20, v21 offset1:1
	v_add_u32_e32 v2, 0x1860, v71
	s_waitcnt vmcnt(9)
	ds_write2_b32 v2, v30, v31 offset1:1
	v_add_u32_e32 v2, 0x1868, v71
	ds_write2_b32 v2, v32, v33 offset1:1
	v_add_u32_e32 v2, 0x1c70, v71
	s_waitcnt vmcnt(8)
	ds_write2_b32 v2, v26, v27 offset1:1
	v_add_u32_e32 v2, 0x1c78, v71
	ds_write2_b32 v2, v28, v29 offset1:1
	v_add_u32_e32 v2, 0x2080, v71
	s_waitcnt vmcnt(7)
	ds_write2_b32 v2, v38, v39 offset1:1
	v_add_u32_e32 v2, 0x2088, v71
	ds_write2_b32 v2, v40, v41 offset1:1
	v_add_u32_e32 v2, 0x2490, v71
	s_waitcnt vmcnt(6)
	ds_write2_b32 v2, v34, v35 offset1:1
	v_add_u32_e32 v2, 0x2498, v71
	ds_write2_b32 v2, v36, v37 offset1:1
	v_add_u32_e32 v2, 0x28a0, v71
	s_waitcnt vmcnt(5)
	ds_write2_b32 v2, v46, v47 offset1:1
	v_add_u32_e32 v2, 0x28a8, v71
	ds_write2_b32 v2, v48, v49 offset1:1
	v_add_u32_e32 v2, 0x2cb0, v71
	s_waitcnt vmcnt(4)
	ds_write2_b32 v2, v42, v43 offset1:1
	v_add_u32_e32 v2, 0x2cb8, v71
	ds_write2_b32 v2, v44, v45 offset1:1
	v_add_u32_e32 v2, 0x30c0, v71
	s_waitcnt vmcnt(3)
	ds_write2_b32 v2, v54, v55 offset1:1
	v_add_u32_e32 v2, 0x30c8, v71
	ds_write2_b32 v2, v56, v57 offset1:1
	v_add_u32_e32 v2, 0x34d0, v71
	s_waitcnt vmcnt(2)
	ds_write2_b32 v2, v50, v51 offset1:1
	v_add_u32_e32 v2, 0x34d8, v71
	ds_write2_b32 v2, v52, v53 offset1:1
	v_add_u32_e32 v2, 0x38e0, v71
	s_waitcnt vmcnt(1)
	ds_write2_b32 v2, v62, v63 offset1:1
	v_add_u32_e32 v2, 0x38e8, v71
	ds_write2_b32 v2, v64, v65 offset1:1
	v_add_u32_e32 v2, 0x3cf0, v71
	s_waitcnt vmcnt(0)
	ds_write2_b32 v2, v58, v59 offset1:1
	v_add_u32_e32 v2, 0x3cf8, v71
	ds_write2_b32 v2, v60, v61 offset1:1
	s_ashr_i32 s17, s16, 31
	s_waitcnt lgkmcnt(0)
	s_lshl_b64 s[38:39], s[16:17], 1
	v_add_u32_e32 v12, 0x400, v78
	ds_read2_b32 v[142:143], v78 offset1:65
	ds_read2_b32 v[144:145], v78 offset0:130 offset1:195
	ds_read2_b32 v[146:147], v12 offset0:4 offset1:69
	ds_read2_b32 v[148:149], v12 offset0:134 offset1:199
	ds_read2_b32 v[150:151], v78 offset0:8 offset1:73
	ds_read2_b32 v[152:153], v78 offset0:138 offset1:203
	ds_read2_b32 v[154:155], v12 offset0:12 offset1:77
	ds_read2_b32 v[156:157], v12 offset0:142 offset1:207
	s_add_u32 s38, s12, s38
	s_waitcnt lgkmcnt(7)
	v_cvt_pk_bf16_f32 v2, v142, v143
	ds_read2_b32 v[142:143], v78 offset0:16 offset1:81
	s_addc_u32 s39, s13, s39
	v_lshlrev_b32_e32 v8, 1, v68
	v_mov_b32_e32 v9, v1
	v_or_b32_e32 v10, s36, v77
	s_waitcnt lgkmcnt(7)
	v_cvt_pk_bf16_f32 v3, v144, v145
	ds_read2_b32 v[144:145], v78 offset0:146 offset1:211
	v_lshl_add_u64 v[8:9], s[38:39], 0, v[8:9]
	v_mul_hi_i32_i24_e32 v11, s0, v10
	v_mul_i32_i24_e32 v10, s0, v10
	s_waitcnt lgkmcnt(7)
	v_cvt_pk_bf16_f32 v4, v146, v147
	ds_read2_b32 v[146:147], v12 offset0:20 offset1:85
	s_waitcnt lgkmcnt(7)
	v_cvt_pk_bf16_f32 v5, v148, v149
	ds_read2_b32 v[148:149], v12 offset0:150 offset1:215
	v_lshl_add_u64 v[10:11], v[10:11], 1, v[8:9]
	global_store_dwordx4 v[10:11], v[2:5], off
	v_or_b32_e32 v10, s36, v79
	v_mul_hi_i32_i24_e32 v11, s0, v10
	s_waitcnt lgkmcnt(7)
; #define LAS __attribute__((address_space(3)))
; __device__ __forceinline__ unsigned cvt_pk_bf16(float lo, float hi) { unsigned r; asm volatile("v_cvt_pk_bf16_f32 %0, %1, %2" : "=v"(r) : "v"(lo), "v"(hi)); return r; }
; template <bool UPPERM> __device__ __forceinline__ void p0_transpose_item(const float* W, int K, int N, bf16_t* WT, const float* gk, LAS float* scr, int item, int lane) {
;     ...
;     for (int j = 0; j < 8; ++j) { const int n = (lane >> 3) + 8 * j; const LAS float* s = scr + (8 * c) * 65 + n;
;         u32x4 o; o.x = cvt_pk_bf16(s[0 * 65], s[1 * 65]); o.y = cvt_pk_bf16(s[2 * 65], s[3 * 65]); o.z = cvt_pk_bf16(s[4 * 65], s[5 * 65]); o.w = cvt_pk_bf16(s[6 * 65], s[7 * 65]);
;         *(u32x4*)(WT + (size_t)(dn0 + (UPPERM ? ((n >> 5) * 64 + (n & 31)) : n)) * K + k0 + 8 * c) = o; }
;     asm volatile("s_waitcnt lgkmcnt(0)" ::: "memory");
	v_cvt_pk_bf16_f32 v2, v150, v151
	ds_read2_b32 v[150:151], v78 offset0:24 offset1:89
	s_waitcnt lgkmcnt(7)
	v_cvt_pk_bf16_f32 v3, v152, v153
	ds_read2_b32 v[152:153], v78 offset0:154 offset1:219
	v_mul_i32_i24_e32 v10, s0, v10
	s_waitcnt lgkmcnt(7)
	v_cvt_pk_bf16_f32 v4, v154, v155
	ds_read2_b32 v[154:155], v12 offset0:28 offset1:93
	s_waitcnt lgkmcnt(7)
	v_cvt_pk_bf16_f32 v5, v156, v157
	ds_read2_b32 v[156:157], v12 offset0:158 offset1:223
	v_lshl_add_u64 v[10:11], v[10:11], 1, v[8:9]
	global_store_dwordx4 v[10:11], v[2:5], off
	v_or_b32_e32 v10, s36, v80
	v_mul_hi_i32_i24_e32 v11, s0, v10
	s_waitcnt lgkmcnt(7)
	v_cvt_pk_bf16_f32 v2, v142, v143
	ds_read2_b32 v[142:143], v78 offset0:32 offset1:97
	s_waitcnt lgkmcnt(7)
	v_cvt_pk_bf16_f32 v3, v144, v145
	ds_read2_b32 v[144:145], v78 offset0:162 offset1:227
	v_mul_i32_i24_e32 v10, s0, v10
	s_waitcnt lgkmcnt(7)
	v_cvt_pk_bf16_f32 v4, v146, v147
	ds_read2_b32 v[146:147], v12 offset0:36 offset1:101
	s_waitcnt lgkmcnt(7)
	v_cvt_pk_bf16_f32 v5, v148, v149
	ds_read2_b32 v[148:149], v12 offset0:166 offset1:231
	v_lshl_add_u64 v[10:11], v[10:11], 1, v[8:9]
	global_store_dwordx4 v[10:11], v[2:5], off
	v_or_b32_e32 v10, s36, v81
	v_mul_hi_i32_i24_e32 v11, s0, v10
	s_waitcnt lgkmcnt(7)
	v_cvt_pk_bf16_f32 v2, v150, v151
	ds_read2_b32 v[150:151], v78 offset0:40 offset1:105
	s_waitcnt lgkmcnt(7)
	v_cvt_pk_bf16_f32 v3, v152, v153
	ds_read2_b32 v[152:153], v78 offset0:170 offset1:235
	v_mul_i32_i24_e32 v10, s0, v10
	s_waitcnt lgkmcnt(7)
	v_cvt_pk_bf16_f32 v4, v154, v155
	ds_read2_b32 v[154:155], v12 offset0:44 offset1:109
	s_waitcnt lgkmcnt(7)
	v_cvt_pk_bf16_f32 v5, v156, v157
	ds_read2_b32 v[156:157], v12 offset0:174 offset1:239
	v_lshl_add_u64 v[10:11], v[10:11], 1, v[8:9]
	global_store_dwordx4 v[10:11], v[2:5], off
	v_or_b32_e32 v10, s36, v82
	v_mul_hi_i32_i24_e32 v11, s0, v10
	s_waitcnt lgkmcnt(7)
	v_cvt_pk_bf16_f32 v2, v142, v143
	ds_read2_b32 v[142:143], v78 offset0:48 offset1:113
	s_waitcnt lgkmcnt(7)
	v_cvt_pk_bf16_f32 v3, v144, v145
	ds_read2_b32 v[144:145], v78 offset0:178 offset1:243
	v_mul_i32_i24_e32 v10, s0, v10
	s_waitcnt lgkmcnt(7)
	v_cvt_pk_bf16_f32 v4, v146, v147
	ds_read2_b32 v[146:147], v12 offset0:52 offset1:117
	s_waitcnt lgkmcnt(7)
	v_cvt_pk_bf16_f32 v5, v148, v149
	ds_read2_b32 v[148:149], v12 offset0:182 offset1:247
	v_lshl_add_u64 v[10:11], v[10:11], 1, v[8:9]
	global_store_dwordx4 v[10:11], v[2:5], off
	v_or_b32_e32 v10, s36, v83
	v_mul_hi_i32_i24_e32 v11, s0, v10
	s_waitcnt lgkmcnt(7)
	v_cvt_pk_bf16_f32 v2, v150, v151
	ds_read2_b32 v[150:151], v78 offset0:56 offset1:121
	s_waitcnt lgkmcnt(7)
	v_cvt_pk_bf16_f32 v3, v152, v153
	ds_read2_b32 v[152:153], v78 offset0:186 offset1:251
	v_mul_i32_i24_e32 v10, s0, v10
	s_waitcnt lgkmcnt(7)
	v_cvt_pk_bf16_f32 v4, v154, v155
	ds_read2_b32 v[154:155], v12 offset0:60 offset1:125
	s_waitcnt lgkmcnt(7)
	v_cvt_pk_bf16_f32 v5, v156, v157
	ds_read2_b32 v[156:157], v12 offset0:190 offset1:255
	v_lshl_add_u64 v[10:11], v[10:11], 1, v[8:9]
	global_store_dwordx4 v[10:11], v[2:5], off
	v_or_b32_e32 v10, s36, v84
	v_mul_hi_i32_i24_e32 v11, s0, v10
	s_waitcnt lgkmcnt(7)
	v_cvt_pk_bf16_f32 v2, v142, v143
	s_waitcnt lgkmcnt(6)
	v_cvt_pk_bf16_f32 v3, v144, v145
	v_mul_i32_i24_e32 v10, s0, v10
	s_waitcnt lgkmcnt(5)
	v_cvt_pk_bf16_f32 v4, v146, v147
	s_waitcnt lgkmcnt(4)
	v_cvt_pk_bf16_f32 v5, v148, v149
	v_lshl_add_u64 v[10:11], v[10:11], 1, v[8:9]
	global_store_dwordx4 v[10:11], v[2:5], off
	s_mov_b64 s[40:41], 0
	s_waitcnt lgkmcnt(3)
	v_cvt_pk_bf16_f32 v2, v150, v151
	s_waitcnt lgkmcnt(2)
	v_cvt_pk_bf16_f32 v3, v152, v153
	s_waitcnt lgkmcnt(1)
	v_cvt_pk_bf16_f32 v4, v154, v155
	s_waitcnt lgkmcnt(0)
	v_cvt_pk_bf16_f32 v5, v156, v157
	v_or_b32_e32 v6, s36, v85
	v_mul_hi_i32_i24_e32 v7, s0, v6
	v_mul_i32_i24_e32 v6, s0, v6
	v_lshl_add_u64 v[6:7], v[6:7], 1, v[8:9]
	global_store_dwordx4 v[6:7], v[2:5], off
	s_waitcnt lgkmcnt(0)
